# plus comb gain multiplies fill DPP wait states, P6 epilogue q written directly, LRU prefetch rows zero-filled only for out-of-range lanes
# speedup vs baseline: 1.0023x; 1.0023x over previous
.LBB0_321:
	s_andn2_b64 vcc, exec, s[46:47]
	s_cbranch_vccnz .LBB0_337
	v_add_u32_e32 v0, 0x180, v123
	v_add_u32_e32 v1, 0x67f, v151
	v_cndmask_b32_e64 v33, v1, v0, s[12:13]
	v_add_u32_e32 v0, -1, v33
	v_cmp_gt_u32_e32 vcc, s50, v0
	s_and_saveexec_b64 s[46:47], vcc
	s_cbranch_execz .Llz_a
	v_mul_u32_u24_e32 v0, s60, v0
	v_mov_b32_e32 v1, v32
	v_lshl_add_u64 v[0:1], v[0:1], 1, v[164:165]
	global_load_dwordx4 v[76:79], v[0:1], off offset:1536
.Llz_a:
	s_xor_b64 exec, exec, s[46:47]
	s_cbranch_execz .Lld_a
	v_mov_b32_e32 v76, 0
	v_mov_b32_e32 v77, 0
	v_mov_b32_e32 v78, 0
	v_mov_b32_e32 v79, 0
.Lld_a:
	s_mov_b64 exec, s[46:47]
	v_mul_u32_u24_e32 v0, s60, v33
	v_mov_b32_e32 v1, v32
	v_lshl_add_u64 v[0:1], v[0:1], 1, v[164:165]
	global_load_dwordx4 v[80:83], v[0:1], off offset:1536
	v_lshl_add_u64 v[0:1], v[0:1], 0, s[40:41]
	v_cmp_gt_u32_e32 vcc, s51, v33
	s_and_saveexec_b64 s[46:47], vcc
	s_cbranch_execz .Llz_c
	global_load_dwordx4 v[72:75], v[0:1], off offset:3584
.Llz_c:
	s_xor_b64 exec, exec, s[46:47]
	s_cbranch_execz .Lld_c
	v_mov_b32_e32 v72, 0
	v_mov_b32_e32 v73, 0
	v_mov_b32_e32 v74, 0
	v_mov_b32_e32 v75, 0
.Lld_c:
	s_mov_b64 exec, s[46:47]
	v_cmp_gt_u32_e32 vcc, s61, v33
	s_and_saveexec_b64 s[46:47], vcc
	s_cbranch_execz .Llz_d
	v_add_co_u32_e32 v0, vcc, 0x1000, v0
	s_nop 1
	v_addc_co_u32_e32 v1, vcc, 0, v1, vcc
	global_load_dwordx4 v[84:87], v[0:1], off offset:3072
.Llz_d:
	s_xor_b64 exec, exec, s[46:47]
	s_cbranch_execz .Lld_d
	v_mov_b32_e32 v84, 0
	v_mov_b32_e32 v85, 0
	v_mov_b32_e32 v86, 0
	v_mov_b32_e32 v87, 0
.Lld_d:
	s_mov_b64 exec, s[46:47]
	v_add_u32_e32 v0, 0x1c0, v123
	v_add_u32_e32 v1, 0x63f, v151
	v_cndmask_b32_e64 v0, v1, v0, s[12:13]
	v_add_u32_e32 v1, -1, v0
	v_cmp_gt_u32_e32 vcc, s50, v1
	s_and_saveexec_b64 s[46:47], vcc
	s_cbranch_execz .Llz_e
	v_mul_u32_u24_e32 v34, s60, v1
	v_mov_b32_e32 v35, v32
	v_lshl_add_u64 v[34:35], v[34:35], 1, v[164:165]
	global_load_dwordx4 v[88:91], v[34:35], off offset:1536
.Llz_e:
	s_xor_b64 exec, exec, s[46:47]
	s_cbranch_execz .Lld_e
	v_mov_b32_e32 v88, 0
	v_mov_b32_e32 v89, 0
	v_mov_b32_e32 v90, 0
	v_mov_b32_e32 v91, 0
.Lld_e:
	s_mov_b64 exec, s[46:47]
	v_cmp_gt_u32_e32 vcc, s50, v0
	s_and_saveexec_b64 s[46:47], vcc
	s_cbranch_execz .Llz_f
	v_mul_u32_u24_e32 v34, s60, v0
	v_mov_b32_e32 v35, v32
	v_lshl_add_u64 v[34:35], v[34:35], 1, v[164:165]
	global_load_dwordx4 v[92:95], v[34:35], off offset:1536
.Llz_f:
	s_xor_b64 exec, exec, s[46:47]
	s_cbranch_execz .Lld_f
	v_mov_b32_e32 v92, 0
	v_mov_b32_e32 v93, 0
	v_mov_b32_e32 v94, 0
	v_mov_b32_e32 v95, 0
.Lld_f:
	s_mov_b64 exec, s[46:47]
	v_add_u32_e32 v1, 1, v0
	v_cmp_gt_u32_e32 vcc, s50, v1
	s_and_saveexec_b64 s[46:47], vcc
	s_cbranch_execz .Llz_g
	v_mul_u32_u24_e32 v34, s60, v1
	v_mov_b32_e32 v35, v32
	v_lshl_add_u64 v[34:35], v[34:35], 1, v[164:165]
	global_load_dwordx4 v[96:99], v[34:35], off offset:1536
.Llz_g:
	s_xor_b64 exec, exec, s[46:47]
	s_cbranch_execz .Lld_g
	v_mov_b32_e32 v96, 0
	v_mov_b32_e32 v97, 0
	v_mov_b32_e32 v98, 0
	v_mov_b32_e32 v99, 0
.Lld_g:
	s_mov_b64 exec, s[46:47]
	v_add_u32_e32 v0, 2, v0
	v_cmp_gt_u32_e32 vcc, s50, v0
	s_and_saveexec_b64 s[46:47], vcc
	s_cbranch_execz .Llz_h
	v_mul_u32_u24_e32 v34, s60, v0
	v_mov_b32_e32 v35, v32
	v_lshl_add_u64 v[34:35], v[34:35], 1, v[164:165]
	global_load_dwordx4 v[100:103], v[34:35], off offset:1536
.Llz_h:
	s_xor_b64 exec, exec, s[46:47]
	s_cbranch_execz .Lld_h
	v_mov_b32_e32 v100, 0
	v_mov_b32_e32 v101, 0
	v_mov_b32_e32 v102, 0
	v_mov_b32_e32 v103, 0
.Lld_h:
	s_mov_b64 exec, s[46:47]
.LBB0_336:
	v_mov_b32_e32 v0, v151
